# fox attention: forget-gate cumsum stored negated (no 32 v_xor/tile), non-diagonal tiles exp score registers directly (no 32 v_mov/tile); on top of pipelined fragment reads + gemm saddr
# speedup vs baseline: 1.0067x; 1.0045x over previous
.LBB0_683:
	s_and_b32 s79, s18, 1
	s_cmp_gt_i32 s78, s77
	s_cbranch_scc1 .LBB0_692
	s_mul_i32 s20, s79, 0x4400
	ds_read_b128 v[80:83], v172
	ds_read_b128 v[84:87], v172 offset:16
	ds_read_b128 v[88:91], v172 offset:64
	ds_read_b128 v[92:95], v172 offset:80
	v_add_u32_e32 v0, s20, v164
	ds_read_b128 v[206:209], v0 offset:8704
	ds_read_b128 v[210:213], v0 offset:8736
	ds_read_b128 v[214:217], v0 offset:8768
	ds_read_b128 v[218:221], v0 offset:8800
	ds_read_b128 v[222:225], v0 offset:8832
	ds_read_b128 v[226:229], v0 offset:8864
	s_waitcnt lgkmcnt(6)
	s_add_i32 s20, s78, 63
	s_cmp_ge_i32 s20, s75
	s_mov_b64 s[56:57], -1
	s_waitcnt lgkmcnt(5)
	v_mfma_f32_32x32x16_bf16 v[80:95], v[206:209], v[140:143], v[80:95]
	ds_read_b128 v[206:209], v0 offset:8896
	s_waitcnt lgkmcnt(5)
	v_mfma_f32_32x32x16_bf16 v[80:95], v[210:213], v[136:139], v[80:95]
	ds_read_b128 v[210:213], v0 offset:8928
	ds_read_b128 v[96:99], v172 offset:128
	ds_read_b128 v[100:103], v172 offset:144
	ds_read_b128 v[104:107], v172 offset:192
	ds_read_b128 v[108:111], v172 offset:208
	s_waitcnt lgkmcnt(9)
	v_mfma_f32_32x32x16_bf16 v[80:95], v[214:217], v[132:135], v[80:95]
	ds_read_b128 v[214:217], v0 offset:17408
	s_waitcnt lgkmcnt(9)
	v_mfma_f32_32x32x16_bf16 v[80:95], v[218:221], v[128:131], v[80:95]
	ds_read_b128 v[218:221], v0 offset:17440
	s_waitcnt lgkmcnt(9)
	v_mfma_f32_32x32x16_bf16 v[80:95], v[222:225], v[124:127], v[80:95]
	ds_read_b128 v[222:225], v0 offset:17472
	s_waitcnt lgkmcnt(9)
	v_mfma_f32_32x32x16_bf16 v[80:95], v[226:229], v[120:123], v[80:95]
	ds_read_b128 v[226:229], v0 offset:17504
	s_waitcnt lgkmcnt(9)
	v_mfma_f32_32x32x16_bf16 v[80:95], v[206:209], v[116:119], v[80:95]
	ds_read_b128 v[206:209], v0 offset:17536
	s_waitcnt lgkmcnt(9)
	v_mfma_f32_32x32x16_bf16 v[80:95], v[210:213], v[112:115], v[80:95]
	ds_read_b128 v[210:213], v0 offset:17568
	s_waitcnt lgkmcnt(6)
	s_waitcnt lgkmcnt(5)
	v_mfma_f32_32x32x16_bf16 v[96:111], v[214:217], v[140:143], v[96:111]
	ds_read_b128 v[214:217], v0 offset:17600
	s_waitcnt lgkmcnt(5)
	v_mfma_f32_32x32x16_bf16 v[96:111], v[218:221], v[136:139], v[96:111]
	ds_read_b128 v[218:221], v0 offset:17632
	s_waitcnt lgkmcnt(5)
	v_mfma_f32_32x32x16_bf16 v[96:111], v[222:225], v[132:135], v[96:111]
	s_waitcnt lgkmcnt(4)
	v_mfma_f32_32x32x16_bf16 v[96:111], v[226:229], v[128:131], v[96:111]
	s_waitcnt lgkmcnt(3)
	v_mfma_f32_32x32x16_bf16 v[96:111], v[206:209], v[124:127], v[96:111]
	s_waitcnt lgkmcnt(2)
	v_mfma_f32_32x32x16_bf16 v[96:111], v[210:213], v[120:123], v[96:111]
	s_waitcnt lgkmcnt(1)
	v_mfma_f32_32x32x16_bf16 v[96:111], v[214:217], v[116:119], v[96:111]
	s_waitcnt lgkmcnt(0)
	v_mfma_f32_32x32x16_bf16 v[96:111], v[218:221], v[112:115], v[96:111]
	s_nop 7
	s_cbranch_scc0 .LBB0_686
	v_add_u32_e32 v0, s78, v148
	v_cmp_le_i32_e32 vcc, v0, v163
	v_add_u32_e32 v175, 2, v0
	v_add_u32_e32 v176, 3, v0
	v_cndmask_b32_e32 v15, v239, v80, vcc
	v_cmp_lt_i32_e32 vcc, v0, v163
	v_add_u32_e32 v177, 4, v0
	v_add_u32_e32 v178, 5, v0
	v_cndmask_b32_e32 v174, v239, v81, vcc
	v_cmp_le_i32_e32 vcc, v175, v163
	v_add_u32_e32 v179, 6, v0
	v_add_u32_e32 v182, 17, v0
	v_cndmask_b32_e32 v175, v239, v82, vcc
	v_cmp_le_i32_e32 vcc, v176, v163
	v_add_u32_e32 v183, 18, v0
	v_add_u32_e32 v184, 19, v0
	v_cndmask_b32_e32 v176, v239, v83, vcc
	v_cmp_le_i32_e32 vcc, v177, v163
	v_add_u32_e32 v185, 20, v0
	v_add_u32_e32 v186, 21, v0
	v_cndmask_b32_e32 v177, v239, v84, vcc
	v_cmp_le_i32_e32 vcc, v178, v163
	v_add_u32_e32 v187, 22, v0
	v_add_u32_e32 v188, 23, v0
	v_cndmask_b32_e32 v178, v239, v85, vcc
	v_cmp_le_i32_e32 vcc, v179, v163
	v_add_u32_e32 v179, 7, v0
	v_add_u32_e32 v191, 33, v0
	v_cndmask_b32_e32 v180, v239, v86, vcc
	v_cmp_le_i32_e32 vcc, v179, v163
	v_add_u32_e32 v179, 16, v0
	v_add_u32_e32 v192, 34, v0
	v_cndmask_b32_e32 v181, v239, v87, vcc
	v_cmp_le_i32_e32 vcc, v179, v163
	v_max3_f32 v14, v15, s23, v174
	v_add_u32_e32 v193, 35, v0
	v_cndmask_b32_e32 v179, v239, v88, vcc
	v_cmp_le_i32_e32 vcc, v182, v163
	v_max3_f32 v14, v14, v175, v176
	v_add_u32_e32 v194, 36, v0
	v_cndmask_b32_e32 v182, v239, v89, vcc
	v_cmp_le_i32_e32 vcc, v183, v163
	v_max3_f32 v14, v14, v177, v178
	v_add_u32_e32 v195, 37, v0
	v_cndmask_b32_e32 v183, v239, v90, vcc
	v_cmp_le_i32_e32 vcc, v184, v163
	v_max3_f32 v14, v14, v180, v181
	v_add_u32_e32 v196, 38, v0
	v_cndmask_b32_e32 v184, v239, v91, vcc
	v_cmp_le_i32_e32 vcc, v185, v163
	v_max3_f32 v14, v14, v179, v182
	v_max3_f32 v14, v14, v183, v184
	v_cndmask_b32_e32 v185, v239, v92, vcc
	v_cmp_le_i32_e32 vcc, v186, v163
	v_add_u32_e32 v197, 49, v0
	v_add_u32_e32 v200, 50, v0
	v_cndmask_b32_e32 v186, v239, v93, vcc
	v_cmp_le_i32_e32 vcc, v187, v163
	v_max3_f32 v14, v14, v185, v186
	v_add_u32_e32 v201, 51, v0
	v_cndmask_b32_e32 v187, v239, v94, vcc
	v_cmp_le_i32_e32 vcc, v188, v163
	v_add_u32_e32 v188, 32, v0
	v_add_u32_e32 v202, 52, v0
	v_cndmask_b32_e32 v189, v239, v95, vcc
	v_cmp_le_i32_e32 vcc, v188, v163
	v_max3_f32 v14, v14, v187, v189
	v_add_u32_e32 v203, 53, v0
	v_cndmask_b32_e32 v188, v239, v96, vcc
	v_cmp_le_i32_e32 vcc, v191, v163
	v_add_u32_e32 v204, 54, v0
	s_mov_b64 s[56:57], 0
	v_cndmask_b32_e32 v191, v239, v97, vcc
	v_cmp_le_i32_e32 vcc, v192, v163
	v_max3_f32 v14, v14, v188, v191
	s_nop 0
	v_cndmask_b32_e32 v192, v239, v98, vcc
	v_cmp_le_i32_e32 vcc, v193, v163
	s_nop 1
	v_cndmask_b32_e32 v193, v239, v99, vcc
	v_cmp_le_i32_e32 vcc, v194, v163
	v_max3_f32 v14, v14, v192, v193
	s_nop 0
	v_cndmask_b32_e32 v194, v239, v100, vcc
	v_cmp_le_i32_e32 vcc, v195, v163
	s_nop 1
	v_cndmask_b32_e32 v195, v239, v101, vcc
	v_cmp_le_i32_e32 vcc, v196, v163
	v_add_u32_e32 v196, 39, v0
	v_max3_f32 v14, v14, v194, v195
	v_cndmask_b32_e32 v198, v239, v102, vcc
	v_cmp_le_i32_e32 vcc, v196, v163
	v_add_u32_e32 v196, 48, v0
	v_add_u32_e32 v0, 55, v0
	v_cndmask_b32_e32 v199, v239, v103, vcc
	v_cmp_le_i32_e32 vcc, v196, v163
	v_max3_f32 v14, v14, v198, v199
	s_nop 0
	v_cndmask_b32_e32 v196, v239, v104, vcc
	v_cmp_le_i32_e32 vcc, v197, v163
	s_nop 1
	v_cndmask_b32_e32 v197, v239, v105, vcc
	v_cmp_le_i32_e32 vcc, v200, v163
	v_max3_f32 v14, v14, v196, v197
	s_nop 0
	v_cndmask_b32_e32 v200, v239, v106, vcc
	v_cmp_le_i32_e32 vcc, v201, v163
	s_nop 1
	v_cndmask_b32_e32 v201, v239, v107, vcc
	v_cmp_le_i32_e32 vcc, v202, v163
	v_max3_f32 v14, v14, v200, v201
	s_nop 0
	v_cndmask_b32_e32 v202, v239, v108, vcc
	v_cmp_le_i32_e32 vcc, v203, v163
	s_nop 1
	v_cndmask_b32_e32 v203, v239, v109, vcc
	v_cmp_le_i32_e32 vcc, v204, v163
	v_max3_f32 v14, v14, v202, v203
	s_nop 0
	v_cndmask_b32_e32 v204, v239, v110, vcc
	v_cmp_le_i32_e32 vcc, v0, v163
	s_nop 1
	v_cndmask_b32_e32 v205, v239, v111, vcc
	v_max3_f32 v0, v14, v204, v205

.LBB0_688:
	v_mov_b32_e32 v14, v0
	v_mov_b32_e32 v240, v0
	s_nop 1
	v_permlane32_swap_b32_e32 v14, v240
	v_cndmask_b32_e64 v14, v14, v240, s[0:1]
	v_max3_f32 v14, v173, v0, v14
	v_sub_f32_e32 v0, v173, v14
	v_exp_f32_e32 v0, v0
	s_nop 0
	v_cmp_neq_f32_e32 vcc, 1.0, v0
	s_cbranch_vccz .LBB0_690
	v_pk_mul_f32 v[78:79], v[78:79], v[0:1] op_sel_hi:[1,0]
	v_pk_mul_f32 v[76:77], v[76:77], v[0:1] op_sel_hi:[1,0]
	v_pk_mul_f32 v[74:75], v[74:75], v[0:1] op_sel_hi:[1,0]
	v_pk_mul_f32 v[72:73], v[72:73], v[0:1] op_sel_hi:[1,0]
	v_pk_mul_f32 v[70:71], v[70:71], v[0:1] op_sel_hi:[1,0]
	v_pk_mul_f32 v[68:69], v[68:69], v[0:1] op_sel_hi:[1,0]
	v_pk_mul_f32 v[66:67], v[66:67], v[0:1] op_sel_hi:[1,0]
	v_pk_mul_f32 v[64:65], v[64:65], v[0:1] op_sel_hi:[1,0]
	v_pk_mul_f32 v[62:63], v[62:63], v[0:1] op_sel_hi:[1,0]
	v_pk_mul_f32 v[60:61], v[60:61], v[0:1] op_sel_hi:[1,0]
	v_pk_mul_f32 v[58:59], v[58:59], v[0:1] op_sel_hi:[1,0]
	v_pk_mul_f32 v[56:57], v[56:57], v[0:1] op_sel_hi:[1,0]
	v_pk_mul_f32 v[54:55], v[54:55], v[0:1] op_sel_hi:[1,0]
	v_pk_mul_f32 v[52:53], v[52:53], v[0:1] op_sel_hi:[1,0]
	v_pk_mul_f32 v[50:51], v[50:51], v[0:1] op_sel_hi:[1,0]
	v_pk_mul_f32 v[48:49], v[48:49], v[0:1] op_sel_hi:[1,0]
	v_pk_mul_f32 v[46:47], v[46:47], v[0:1] op_sel_hi:[1,0]
	v_pk_mul_f32 v[44:45], v[44:45], v[0:1] op_sel_hi:[1,0]
	v_pk_mul_f32 v[42:43], v[42:43], v[0:1] op_sel_hi:[1,0]
	v_pk_mul_f32 v[40:41], v[40:41], v[0:1] op_sel_hi:[1,0]
	v_pk_mul_f32 v[38:39], v[38:39], v[0:1] op_sel_hi:[1,0]
	v_pk_mul_f32 v[36:37], v[36:37], v[0:1] op_sel_hi:[1,0]
	v_pk_mul_f32 v[34:35], v[34:35], v[0:1] op_sel_hi:[1,0]
	v_pk_mul_f32 v[32:33], v[32:33], v[0:1] op_sel_hi:[1,0]
	v_pk_mul_f32 v[30:31], v[30:31], v[0:1] op_sel_hi:[1,0]
	v_pk_mul_f32 v[28:29], v[28:29], v[0:1] op_sel_hi:[1,0]
	v_pk_mul_f32 v[26:27], v[26:27], v[0:1] op_sel_hi:[1,0]
	v_pk_mul_f32 v[24:25], v[24:25], v[0:1] op_sel_hi:[1,0]
	v_pk_mul_f32 v[22:23], v[22:23], v[0:1] op_sel_hi:[1,0]
	v_pk_mul_f32 v[20:21], v[20:21], v[0:1] op_sel_hi:[1,0]
	v_pk_mul_f32 v[18:19], v[18:19], v[0:1] op_sel_hi:[1,0]
	v_pk_mul_f32 v[16:17], v[16:17], v[0:1] op_sel_hi:[1,0]
.LBB0_690:
	s_and_b64 vcc, exec, s[56:57]
	s_cbranch_vccz .Lfox_exp_masked
	v_sub_f32_e32 v240, v111, v14
	v_sub_f32_e32 v241, v110, v14
	v_sub_f32_e32 v242, v109, v14
	v_sub_f32_e32 v243, v108, v14
	v_sub_f32_e32 v244, v107, v14
	v_sub_f32_e32 v245, v106, v14
	v_sub_f32_e32 v246, v105, v14
	v_sub_f32_e32 v247, v104, v14
	v_exp_f32_e32 v187, v240
	v_exp_f32_e32 v186, v241
	v_exp_f32_e32 v185, v242
	v_exp_f32_e32 v184, v243
	v_exp_f32_e32 v183, v244
	v_exp_f32_e32 v182, v245
	v_exp_f32_e32 v181, v246
	v_exp_f32_e32 v180, v247
	v_sub_f32_e32 v240, v103, v14
	v_sub_f32_e32 v241, v102, v14
	v_sub_f32_e32 v242, v101, v14
	v_sub_f32_e32 v243, v100, v14
	v_sub_f32_e32 v244, v99, v14
	v_sub_f32_e32 v245, v98, v14
	v_sub_f32_e32 v246, v97, v14
	v_sub_f32_e32 v247, v96, v14
	v_exp_f32_e32 v179, v240
	v_exp_f32_e32 v178, v241
	v_exp_f32_e32 v177, v242
	v_exp_f32_e32 v176, v243
	v_exp_f32_e32 v175, v244
	v_exp_f32_e32 v174, v245
	v_exp_f32_e32 v173, v246
	v_exp_f32_e32 v111, v247
	v_sub_f32_e32 v240, v80, v14
	v_sub_f32_e32 v241, v81, v14
	v_sub_f32_e32 v242, v82, v14
	v_sub_f32_e32 v243, v83, v14
	v_sub_f32_e32 v244, v84, v14
	v_sub_f32_e32 v245, v85, v14
	v_sub_f32_e32 v246, v86, v14
	v_sub_f32_e32 v247, v87, v14
	v_exp_f32_e32 v15, v240
	v_exp_f32_e32 v96, v241
	v_exp_f32_e32 v97, v242
	v_exp_f32_e32 v98, v243
	v_exp_f32_e32 v99, v244
	v_exp_f32_e32 v100, v245
	v_exp_f32_e32 v101, v246
	v_exp_f32_e32 v102, v247
	v_sub_f32_e32 v240, v88, v14
	v_sub_f32_e32 v241, v89, v14
	v_sub_f32_e32 v242, v90, v14
	v_sub_f32_e32 v243, v91, v14
	v_sub_f32_e32 v244, v92, v14
	v_sub_f32_e32 v245, v93, v14
	v_sub_f32_e32 v246, v94, v14
	v_sub_f32_e32 v247, v95, v14
	v_exp_f32_e32 v103, v240
	v_exp_f32_e32 v104, v241
	v_exp_f32_e32 v105, v242
	v_exp_f32_e32 v106, v243
	v_exp_f32_e32 v107, v244
	v_exp_f32_e32 v108, v245
	v_exp_f32_e32 v109, v246
	v_exp_f32_e32 v110, v247
	s_branch .Lfox_cvt

.Lfox_cvt:
	v_cvt_pk_bf16_f32 v80, v15, v96
	v_cvt_pk_bf16_f32 v81, v97, v98
	v_cvt_pk_bf16_f32 v82, v99, v100
	v_cvt_pk_bf16_f32 v83, v101, v102
	v_cvt_pk_bf16_f32 v84, v103, v104
	v_cvt_pk_bf16_f32 v85, v105, v106
	v_cvt_pk_bf16_f32 v86, v107, v108
	v_cvt_pk_bf16_f32 v87, v109, v110
	v_cvt_pk_bf16_f32 v88, v111, v173
	v_cvt_pk_bf16_f32 v89, v174, v175
	v_cvt_pk_bf16_f32 v90, v176, v177
	v_cvt_pk_bf16_f32 v91, v178, v179
	v_cvt_pk_bf16_f32 v92, v180, v181
	v_cvt_pk_bf16_f32 v93, v182, v183
	v_cvt_pk_bf16_f32 v94, v184, v185
	v_cvt_pk_bf16_f32 v95, v186, v187
	s_andn2_b64 vcc, exec, s[52:53]
	s_mov_b64 s[70:71], -1
	s_cbranch_vccnz .LBB0_693
	s_mul_i32 s20, s74, 0x4800
	v_add_u32_e32 v188, s20, v162
	s_mov_b64 s[70:71], 0
	ds_read_b128 v[206:209], v188 offset:43520
	ds_read_b128 v[210:213], v188 offset:43552
	ds_read_b128 v[214:217], v188 offset:43584
	ds_read_b128 v[218:221], v188 offset:43616
	ds_read_b128 v[222:225], v188 offset:48128
	ds_read_b128 v[226:229], v188 offset:48160
	s_waitcnt lgkmcnt(5)
	v_mfma_f32_32x32x16_bf16 v[64:79], v[206:209], v[80:83], v[64:79]
	ds_read_b128 v[206:209], v188 offset:48192
	s_waitcnt lgkmcnt(5)
	v_mfma_f32_32x32x16_bf16 v[64:79], v[210:213], v[84:87], v[64:79]
	ds_read_b128 v[210:213], v188 offset:48224
	s_waitcnt lgkmcnt(5)
	v_mfma_f32_32x32x16_bf16 v[64:79], v[214:217], v[88:91], v[64:79]
	ds_read_b128 v[214:217], v188 offset:52736
	s_waitcnt lgkmcnt(5)
	v_mfma_f32_32x32x16_bf16 v[64:79], v[218:221], v[92:95], v[64:79]
	ds_read_b128 v[218:221], v188 offset:52768
	s_waitcnt lgkmcnt(5)
	v_mfma_f32_32x32x16_bf16 v[48:63], v[222:225], v[80:83], v[48:63]
	ds_read_b128 v[222:225], v188 offset:52800
	s_waitcnt lgkmcnt(5)
	v_mfma_f32_32x32x16_bf16 v[48:63], v[226:229], v[84:87], v[48:63]
	ds_read_b128 v[226:229], v188 offset:52832
	s_waitcnt lgkmcnt(5)
	v_mfma_f32_32x32x16_bf16 v[48:63], v[206:209], v[88:91], v[48:63]
	ds_read_b128 v[206:209], v188 offset:57344
	s_waitcnt lgkmcnt(5)
	v_mfma_f32_32x32x16_bf16 v[48:63], v[210:213], v[92:95], v[48:63]
	ds_read_b128 v[210:213], v188 offset:57376
	s_waitcnt lgkmcnt(5)
	v_mfma_f32_32x32x16_bf16 v[32:47], v[214:217], v[80:83], v[32:47]
	ds_read_b128 v[214:217], v188 offset:57408
	s_waitcnt lgkmcnt(5)
	v_mfma_f32_32x32x16_bf16 v[32:47], v[218:221], v[84:87], v[32:47]
	ds_read_b128 v[218:221], v188 offset:57440
	s_waitcnt lgkmcnt(5)
	v_mfma_f32_32x32x16_bf16 v[32:47], v[222:225], v[88:91], v[32:47]
	s_waitcnt lgkmcnt(4)
	v_mfma_f32_32x32x16_bf16 v[32:47], v[226:229], v[92:95], v[32:47]
	s_waitcnt lgkmcnt(3)
	v_mfma_f32_32x32x16_bf16 v[16:31], v[206:209], v[80:83], v[16:31]
	s_waitcnt lgkmcnt(2)
	v_mfma_f32_32x32x16_bf16 v[16:31], v[210:213], v[84:87], v[16:31]
	s_waitcnt lgkmcnt(1)
	v_mfma_f32_32x32x16_bf16 v[16:31], v[214:217], v[88:91], v[16:31]
	s_waitcnt lgkmcnt(0)
	v_mfma_f32_32x32x16_bf16 v[16:31], v[218:221], v[92:95], v[16:31]
	s_branch .LBB0_694
